# scan: stages X and S merged - waves 4-7 solve the triangular system in registers after the G' MFMAs with DPP row broadcast (f32), waves 0-3 run PREP quarters; one barrier fewer per chunk
# speedup vs baseline: 1.0014x; 1.0014x over previous
.Lsx0_c:
	s_or_b64 exec, exec, s[2:3]
	v_mov_b32_e32 v22, 0
	v_mov_b32_e32 v23, 0
	v_mov_b32_e32 v24, 0
	v_mov_b32_e32 v25, 0
	s_and_saveexec_b64 s[2:3], s[56:57]
	s_cbranch_execz .LBB0_403
	ds_read_b128 v[48:51], v174
	ds_read_b128 v[60:63], v192 offset:49152
	ds_read_b128 v[52:55], v174 offset:64
	ds_read_b128 v[64:67], v192 offset:49216
	ds_read_b128 v[56:59], v175
	ds_read_b128 v[68:71], v199
	ds_read_b128 v[72:75], v192 offset:58368
	ds_read_b128 v[76:79], v192 offset:58432
	ds_read_b128 v[80:83], v151
	ds_read_b128 v[84:87], v151 offset:16
	ds_read_b128 v[88:91], v151 offset:32
	ds_read_b128 v[92:95], v151 offset:48
	s_waitcnt lgkmcnt(10)
	v_mfma_f32_16x16x32_bf16 v[30:33], v[48:51], v[60:63], 0
	s_waitcnt lgkmcnt(8)
	v_mfma_f32_16x16x32_bf16 v[30:33], v[52:55], v[64:67], v[30:33]
	s_waitcnt lgkmcnt(6)
	v_mfma_f32_16x16x32_bf16 v[30:33], v[56:59], v[68:71], v[30:33]
	s_waitcnt lgkmcnt(5)
	v_mfma_f32_16x16x32_bf16 v[22:25], v[48:51], v[72:75], 0
	s_waitcnt lgkmcnt(4)
	v_mfma_f32_16x16x32_bf16 v[22:25], v[52:55], v[76:79], v[22:25]
	s_cmp_lg_u32 s21, 0
	s_cbranch_scc0 .Lsx0_d
	v_cvt_pk_bf16_f32 v240, v236, v237
	global_store_dword v[238:239], v240, off
.Lsx0_d:
	s_waitcnt lgkmcnt(0)
	s_nop 7
	v_fmac_f32_dpp v30, v30, v80 row_newbcast:0 row_mask:0xf bank_mask:0xf
	v_fmac_f32_dpp v31, v31, v80 row_newbcast:0 row_mask:0xf bank_mask:0xf
	v_fmac_f32_dpp v32, v32, v80 row_newbcast:0 row_mask:0xf bank_mask:0xf
	v_fmac_f32_dpp v33, v33, v80 row_newbcast:0 row_mask:0xf bank_mask:0xf
	v_fmac_f32_dpp v30, v30, v81 row_newbcast:1 row_mask:0xf bank_mask:0xf
	v_fmac_f32_dpp v31, v31, v81 row_newbcast:1 row_mask:0xf bank_mask:0xf
	v_fmac_f32_dpp v32, v32, v81 row_newbcast:1 row_mask:0xf bank_mask:0xf
	v_fmac_f32_dpp v33, v33, v81 row_newbcast:1 row_mask:0xf bank_mask:0xf
	v_fmac_f32_dpp v30, v30, v82 row_newbcast:2 row_mask:0xf bank_mask:0xf
	v_fmac_f32_dpp v31, v31, v82 row_newbcast:2 row_mask:0xf bank_mask:0xf
	v_fmac_f32_dpp v32, v32, v82 row_newbcast:2 row_mask:0xf bank_mask:0xf
	v_fmac_f32_dpp v33, v33, v82 row_newbcast:2 row_mask:0xf bank_mask:0xf
	v_fmac_f32_dpp v30, v30, v83 row_newbcast:3 row_mask:0xf bank_mask:0xf
	v_fmac_f32_dpp v31, v31, v83 row_newbcast:3 row_mask:0xf bank_mask:0xf
	v_fmac_f32_dpp v32, v32, v83 row_newbcast:3 row_mask:0xf bank_mask:0xf
	v_fmac_f32_dpp v33, v33, v83 row_newbcast:3 row_mask:0xf bank_mask:0xf
	v_fmac_f32_dpp v30, v30, v84 row_newbcast:4 row_mask:0xf bank_mask:0xf
	v_fmac_f32_dpp v31, v31, v84 row_newbcast:4 row_mask:0xf bank_mask:0xf
	v_fmac_f32_dpp v32, v32, v84 row_newbcast:4 row_mask:0xf bank_mask:0xf
	v_fmac_f32_dpp v33, v33, v84 row_newbcast:4 row_mask:0xf bank_mask:0xf
	v_fmac_f32_dpp v30, v30, v85 row_newbcast:5 row_mask:0xf bank_mask:0xf
	v_fmac_f32_dpp v31, v31, v85 row_newbcast:5 row_mask:0xf bank_mask:0xf
	v_fmac_f32_dpp v32, v32, v85 row_newbcast:5 row_mask:0xf bank_mask:0xf
	v_fmac_f32_dpp v33, v33, v85 row_newbcast:5 row_mask:0xf bank_mask:0xf
	v_fmac_f32_dpp v30, v30, v86 row_newbcast:6 row_mask:0xf bank_mask:0xf
	v_fmac_f32_dpp v31, v31, v86 row_newbcast:6 row_mask:0xf bank_mask:0xf
	v_fmac_f32_dpp v32, v32, v86 row_newbcast:6 row_mask:0xf bank_mask:0xf
	v_fmac_f32_dpp v33, v33, v86 row_newbcast:6 row_mask:0xf bank_mask:0xf
	v_fmac_f32_dpp v30, v30, v87 row_newbcast:7 row_mask:0xf bank_mask:0xf
	v_fmac_f32_dpp v31, v31, v87 row_newbcast:7 row_mask:0xf bank_mask:0xf
	v_fmac_f32_dpp v32, v32, v87 row_newbcast:7 row_mask:0xf bank_mask:0xf
	v_fmac_f32_dpp v33, v33, v87 row_newbcast:7 row_mask:0xf bank_mask:0xf
	v_fmac_f32_dpp v30, v30, v88 row_newbcast:8 row_mask:0xf bank_mask:0xf
	v_fmac_f32_dpp v31, v31, v88 row_newbcast:8 row_mask:0xf bank_mask:0xf
	v_fmac_f32_dpp v32, v32, v88 row_newbcast:8 row_mask:0xf bank_mask:0xf
	v_fmac_f32_dpp v33, v33, v88 row_newbcast:8 row_mask:0xf bank_mask:0xf
	v_fmac_f32_dpp v30, v30, v89 row_newbcast:9 row_mask:0xf bank_mask:0xf
	v_fmac_f32_dpp v31, v31, v89 row_newbcast:9 row_mask:0xf bank_mask:0xf
	v_fmac_f32_dpp v32, v32, v89 row_newbcast:9 row_mask:0xf bank_mask:0xf
	v_fmac_f32_dpp v33, v33, v89 row_newbcast:9 row_mask:0xf bank_mask:0xf
	v_fmac_f32_dpp v30, v30, v90 row_newbcast:10 row_mask:0xf bank_mask:0xf
	v_fmac_f32_dpp v31, v31, v90 row_newbcast:10 row_mask:0xf bank_mask:0xf
	v_fmac_f32_dpp v32, v32, v90 row_newbcast:10 row_mask:0xf bank_mask:0xf
	v_fmac_f32_dpp v33, v33, v90 row_newbcast:10 row_mask:0xf bank_mask:0xf
	v_fmac_f32_dpp v30, v30, v91 row_newbcast:11 row_mask:0xf bank_mask:0xf
	v_fmac_f32_dpp v31, v31, v91 row_newbcast:11 row_mask:0xf bank_mask:0xf
	v_fmac_f32_dpp v32, v32, v91 row_newbcast:11 row_mask:0xf bank_mask:0xf
	v_fmac_f32_dpp v33, v33, v91 row_newbcast:11 row_mask:0xf bank_mask:0xf
	v_fmac_f32_dpp v30, v30, v92 row_newbcast:12 row_mask:0xf bank_mask:0xf
	v_fmac_f32_dpp v31, v31, v92 row_newbcast:12 row_mask:0xf bank_mask:0xf
	v_fmac_f32_dpp v32, v32, v92 row_newbcast:12 row_mask:0xf bank_mask:0xf
	v_fmac_f32_dpp v33, v33, v92 row_newbcast:12 row_mask:0xf bank_mask:0xf
	v_fmac_f32_dpp v30, v30, v93 row_newbcast:13 row_mask:0xf bank_mask:0xf
	v_fmac_f32_dpp v31, v31, v93 row_newbcast:13 row_mask:0xf bank_mask:0xf
	v_fmac_f32_dpp v32, v32, v93 row_newbcast:13 row_mask:0xf bank_mask:0xf
	v_fmac_f32_dpp v33, v33, v93 row_newbcast:13 row_mask:0xf bank_mask:0xf
	v_fmac_f32_dpp v30, v30, v94 row_newbcast:14 row_mask:0xf bank_mask:0xf
	v_fmac_f32_dpp v31, v31, v94 row_newbcast:14 row_mask:0xf bank_mask:0xf
	v_fmac_f32_dpp v32, v32, v94 row_newbcast:14 row_mask:0xf bank_mask:0xf
	v_fmac_f32_dpp v33, v33, v94 row_newbcast:14 row_mask:0xf bank_mask:0xf
	v_lshrrev_b32_e32 v82, 6, v198
	v_mul_u32_u24_e32 v82, 0x500, v82
	v_mad_u32_u24 v82, v145, 20, v82
	v_and_b32_e32 v83, 15, v198
	v_lshl_add_u32 v82, v83, 1, v82
	v_add_u32_e32 v82, 0x10a00, v82
	v_cvt_pk_bf16_f32 v80, v30, v31
	v_cvt_pk_bf16_f32 v81, v32, v33
	ds_write_b16 v82, v80 offset:0
	ds_write_b16_d16_hi v82, v80 offset:80
	ds_write_b16 v82, v81 offset:160
	ds_write_b16_d16_hi v82, v81 offset:240
.LBB0_403:
	s_or_b64 exec, exec, s[2:3]
	s_waitcnt lgkmcnt(0)
	s_and_saveexec_b64 s[2:3], s[56:57]
	s_cbranch_execz .Lis0c
	s_cmp_gt_u32 s36, 62
	s_cbranch_scc1 .Lcp0
	s_waitcnt vmcnt(5)
	v_lshlrev_b32_e32 v136, 16, v1
	v_and_b32_e32 v137, 0xffff0000, v1
	v_pk_mul_f32 v[124:125], v[102:103], v[136:137]
	s_waitcnt vmcnt(2)
	v_lshlrev_b32_e32 v126, 16, v3
	s_waitcnt vmcnt(1)
	v_pk_mul_f32 v[124:125], v[108:109], v[124:125] op_sel_hi:[0,1]
	v_and_b32_e32 v127, 0xffff0000, v3
	v_lshlrev_b32_e32 v130, 16, v4
	v_and_b32_e32 v131, 0xffff0000, v4
	v_pk_add_f32 v[128:129], v[130:131], -1.0 op_sel_hi:[1,0]
	v_pk_mul_f32 v[130:131], v[130:131], v[124:125] neg_lo:[0,1] neg_hi:[0,1]
	v_pk_fma_f32 v[128:129], v[104:105], v[128:129], 1.0 op_sel_hi:[1,1,0]
	s_nop 0
	v_pk_mul_f32 v[128:129], v[128:129], v[136:137]
	v_lshlrev_b32_e32 v132, 16, v0
	v_and_b32_e32 v133, 0xffff0000, v0
	v_lshlrev_b32_e32 v134, 16, v2
	v_and_b32_e32 v135, 0xffff0000, v2

.LBB0_405:
	v_lshrrev_b32_e32 v122, 6, v198
	s_nop 0
	v_readfirstlane_b32 s98, v122
	s_nop 3
	s_cmp_eq_u32 s98, 0
	s_cbranch_scc1 .Lpq0_q0
	s_cmp_eq_u32 s98, 1
	s_cbranch_scc1 .Lpq0_q1
	s_cmp_eq_u32 s98, 2
	s_cbranch_scc1 .Lpq0_q2
	s_cmp_eq_u32 s98, 3
	s_cbranch_scc1 .Lpq0_q3
	s_branch .Lpq0_end

.Lsx1_c:
	s_or_b64 exec, exec, s[74:75]
	v_mov_b32_e32 v22, 0
	v_mov_b32_e32 v23, 0
	v_mov_b32_e32 v24, 0
	v_mov_b32_e32 v25, 0
	s_and_saveexec_b64 s[74:75], s[56:57]
	s_cbranch_execz .LBB0_432
	ds_read_b128 v[48:51], v174
	ds_read_b128 v[60:63], v192 offset:51456
	ds_read_b128 v[52:55], v174 offset:64
	ds_read_b128 v[64:67], v192 offset:51520
	ds_read_b128 v[56:59], v175 offset:5120
	ds_read_b128 v[68:71], v199
	ds_read_b128 v[72:75], v192 offset:60672
	ds_read_b128 v[76:79], v192 offset:60736
	ds_read_b128 v[80:83], v151
	ds_read_b128 v[84:87], v151 offset:16
	ds_read_b128 v[88:91], v151 offset:32
	ds_read_b128 v[92:95], v151 offset:48
	s_waitcnt lgkmcnt(10)
	v_mfma_f32_16x16x32_bf16 v[30:33], v[48:51], v[60:63], 0
	s_waitcnt lgkmcnt(8)
	v_mfma_f32_16x16x32_bf16 v[30:33], v[52:55], v[64:67], v[30:33]
	s_waitcnt lgkmcnt(6)
	v_mfma_f32_16x16x32_bf16 v[30:33], v[56:59], v[68:71], v[30:33]
	s_waitcnt lgkmcnt(5)
	v_mfma_f32_16x16x32_bf16 v[22:25], v[48:51], v[72:75], 0
	s_waitcnt lgkmcnt(4)
	v_mfma_f32_16x16x32_bf16 v[22:25], v[52:55], v[76:79], v[22:25]
	v_cvt_pk_bf16_f32 v240, v236, v237
	global_store_dword v[238:239], v240, off
	s_waitcnt lgkmcnt(0)
	s_nop 7
	v_fmac_f32_dpp v30, v30, v80 row_newbcast:0 row_mask:0xf bank_mask:0xf
	v_fmac_f32_dpp v31, v31, v80 row_newbcast:0 row_mask:0xf bank_mask:0xf
	v_fmac_f32_dpp v32, v32, v80 row_newbcast:0 row_mask:0xf bank_mask:0xf
	v_fmac_f32_dpp v33, v33, v80 row_newbcast:0 row_mask:0xf bank_mask:0xf
	v_fmac_f32_dpp v30, v30, v81 row_newbcast:1 row_mask:0xf bank_mask:0xf
	v_fmac_f32_dpp v31, v31, v81 row_newbcast:1 row_mask:0xf bank_mask:0xf
	v_fmac_f32_dpp v32, v32, v81 row_newbcast:1 row_mask:0xf bank_mask:0xf
	v_fmac_f32_dpp v33, v33, v81 row_newbcast:1 row_mask:0xf bank_mask:0xf
	v_fmac_f32_dpp v30, v30, v82 row_newbcast:2 row_mask:0xf bank_mask:0xf
	v_fmac_f32_dpp v31, v31, v82 row_newbcast:2 row_mask:0xf bank_mask:0xf
	v_fmac_f32_dpp v32, v32, v82 row_newbcast:2 row_mask:0xf bank_mask:0xf
	v_fmac_f32_dpp v33, v33, v82 row_newbcast:2 row_mask:0xf bank_mask:0xf
	v_fmac_f32_dpp v30, v30, v83 row_newbcast:3 row_mask:0xf bank_mask:0xf
	v_fmac_f32_dpp v31, v31, v83 row_newbcast:3 row_mask:0xf bank_mask:0xf
	v_fmac_f32_dpp v32, v32, v83 row_newbcast:3 row_mask:0xf bank_mask:0xf
	v_fmac_f32_dpp v33, v33, v83 row_newbcast:3 row_mask:0xf bank_mask:0xf
	v_fmac_f32_dpp v30, v30, v84 row_newbcast:4 row_mask:0xf bank_mask:0xf
	v_fmac_f32_dpp v31, v31, v84 row_newbcast:4 row_mask:0xf bank_mask:0xf
	v_fmac_f32_dpp v32, v32, v84 row_newbcast:4 row_mask:0xf bank_mask:0xf
	v_fmac_f32_dpp v33, v33, v84 row_newbcast:4 row_mask:0xf bank_mask:0xf
	v_fmac_f32_dpp v30, v30, v85 row_newbcast:5 row_mask:0xf bank_mask:0xf
	v_fmac_f32_dpp v31, v31, v85 row_newbcast:5 row_mask:0xf bank_mask:0xf
	v_fmac_f32_dpp v32, v32, v85 row_newbcast:5 row_mask:0xf bank_mask:0xf
	v_fmac_f32_dpp v33, v33, v85 row_newbcast:5 row_mask:0xf bank_mask:0xf
	v_fmac_f32_dpp v30, v30, v86 row_newbcast:6 row_mask:0xf bank_mask:0xf
	v_fmac_f32_dpp v31, v31, v86 row_newbcast:6 row_mask:0xf bank_mask:0xf
	v_fmac_f32_dpp v32, v32, v86 row_newbcast:6 row_mask:0xf bank_mask:0xf
	v_fmac_f32_dpp v33, v33, v86 row_newbcast:6 row_mask:0xf bank_mask:0xf
	v_fmac_f32_dpp v30, v30, v87 row_newbcast:7 row_mask:0xf bank_mask:0xf
	v_fmac_f32_dpp v31, v31, v87 row_newbcast:7 row_mask:0xf bank_mask:0xf
	v_fmac_f32_dpp v32, v32, v87 row_newbcast:7 row_mask:0xf bank_mask:0xf
	v_fmac_f32_dpp v33, v33, v87 row_newbcast:7 row_mask:0xf bank_mask:0xf
	v_fmac_f32_dpp v30, v30, v88 row_newbcast:8 row_mask:0xf bank_mask:0xf
	v_fmac_f32_dpp v31, v31, v88 row_newbcast:8 row_mask:0xf bank_mask:0xf
	v_fmac_f32_dpp v32, v32, v88 row_newbcast:8 row_mask:0xf bank_mask:0xf
	v_fmac_f32_dpp v33, v33, v88 row_newbcast:8 row_mask:0xf bank_mask:0xf
	v_fmac_f32_dpp v30, v30, v89 row_newbcast:9 row_mask:0xf bank_mask:0xf
	v_fmac_f32_dpp v31, v31, v89 row_newbcast:9 row_mask:0xf bank_mask:0xf
	v_fmac_f32_dpp v32, v32, v89 row_newbcast:9 row_mask:0xf bank_mask:0xf
	v_fmac_f32_dpp v33, v33, v89 row_newbcast:9 row_mask:0xf bank_mask:0xf
	v_fmac_f32_dpp v30, v30, v90 row_newbcast:10 row_mask:0xf bank_mask:0xf
	v_fmac_f32_dpp v31, v31, v90 row_newbcast:10 row_mask:0xf bank_mask:0xf
	v_fmac_f32_dpp v32, v32, v90 row_newbcast:10 row_mask:0xf bank_mask:0xf
	v_fmac_f32_dpp v33, v33, v90 row_newbcast:10 row_mask:0xf bank_mask:0xf
	v_fmac_f32_dpp v30, v30, v91 row_newbcast:11 row_mask:0xf bank_mask:0xf
	v_fmac_f32_dpp v31, v31, v91 row_newbcast:11 row_mask:0xf bank_mask:0xf
	v_fmac_f32_dpp v32, v32, v91 row_newbcast:11 row_mask:0xf bank_mask:0xf
	v_fmac_f32_dpp v33, v33, v91 row_newbcast:11 row_mask:0xf bank_mask:0xf
	v_fmac_f32_dpp v30, v30, v92 row_newbcast:12 row_mask:0xf bank_mask:0xf
	v_fmac_f32_dpp v31, v31, v92 row_newbcast:12 row_mask:0xf bank_mask:0xf
	v_fmac_f32_dpp v32, v32, v92 row_newbcast:12 row_mask:0xf bank_mask:0xf
	v_fmac_f32_dpp v33, v33, v92 row_newbcast:12 row_mask:0xf bank_mask:0xf
	v_fmac_f32_dpp v30, v30, v93 row_newbcast:13 row_mask:0xf bank_mask:0xf
	v_fmac_f32_dpp v31, v31, v93 row_newbcast:13 row_mask:0xf bank_mask:0xf
	v_fmac_f32_dpp v32, v32, v93 row_newbcast:13 row_mask:0xf bank_mask:0xf
	v_fmac_f32_dpp v33, v33, v93 row_newbcast:13 row_mask:0xf bank_mask:0xf
	v_fmac_f32_dpp v30, v30, v94 row_newbcast:14 row_mask:0xf bank_mask:0xf
	v_fmac_f32_dpp v31, v31, v94 row_newbcast:14 row_mask:0xf bank_mask:0xf
	v_fmac_f32_dpp v32, v32, v94 row_newbcast:14 row_mask:0xf bank_mask:0xf
	v_fmac_f32_dpp v33, v33, v94 row_newbcast:14 row_mask:0xf bank_mask:0xf
	v_lshrrev_b32_e32 v82, 6, v198
	v_mul_u32_u24_e32 v82, 0x500, v82
	v_mad_u32_u24 v82, v145, 20, v82
	v_and_b32_e32 v83, 15, v198
	v_lshl_add_u32 v82, v83, 1, v82
	v_add_u32_e32 v82, 0x10a00, v82
	v_cvt_pk_bf16_f32 v80, v30, v31
	v_cvt_pk_bf16_f32 v81, v32, v33
	ds_write_b16 v82, v80 offset:5120
	ds_write_b16_d16_hi v82, v80 offset:5200
	ds_write_b16 v82, v81 offset:5280
	ds_write_b16_d16_hi v82, v81 offset:5360
.LBB0_432:
	s_or_b64 exec, exec, s[74:75]
	s_waitcnt lgkmcnt(0)
	s_and_saveexec_b64 s[74:75], s[56:57]
	s_cbranch_execz .Lis1c
	s_cmp_gt_u32 s36, 62
	s_cbranch_scc1 .Lcp1
	s_waitcnt vmcnt(5)
	v_lshlrev_b32_e32 v136, 16, v6
	v_and_b32_e32 v137, 0xffff0000, v6
	v_pk_mul_f32 v[124:125], v[102:103], v[136:137]
	s_waitcnt vmcnt(3)
	v_lshlrev_b32_e32 v126, 16, v8
	s_waitcnt vmcnt(1)
	v_pk_mul_f32 v[124:125], v[110:111], v[124:125] op_sel_hi:[0,1]
	v_and_b32_e32 v127, 0xffff0000, v8
	v_lshlrev_b32_e32 v130, 16, v9
	v_and_b32_e32 v131, 0xffff0000, v9
	v_pk_add_f32 v[128:129], v[130:131], -1.0 op_sel_hi:[1,0]
	v_pk_mul_f32 v[130:131], v[130:131], v[124:125] neg_lo:[0,1] neg_hi:[0,1]
	v_pk_fma_f32 v[128:129], v[104:105], v[128:129], 1.0 op_sel_hi:[1,1,0]
	s_nop 0
	v_pk_mul_f32 v[128:129], v[128:129], v[136:137]
	v_lshlrev_b32_e32 v132, 16, v5
	v_and_b32_e32 v133, 0xffff0000, v5
	v_lshlrev_b32_e32 v134, 16, v7
	v_and_b32_e32 v135, 0xffff0000, v7

.LBB0_434:
	v_lshrrev_b32_e32 v122, 6, v198
	s_nop 0
	v_readfirstlane_b32 s98, v122
	s_nop 3
	s_cmpk_lt_u32 s20, 0x7f
	s_cbranch_scc0 .Lpq1_end
	s_cmp_eq_u32 s98, 0
	s_cbranch_scc1 .Lpq1_q0
	s_cmp_eq_u32 s98, 1
	s_cbranch_scc1 .Lpq1_q1
	s_cmp_eq_u32 s98, 2
	s_cbranch_scc1 .Lpq1_q2
	s_cmp_eq_u32 s98, 3
	s_cbranch_scc1 .Lpq1_q3
	s_branch .Lpq1_end
